# final-norm work queue: next round's queue atomic read at next round start instead of waited immediately
# baseline (speedup 1.0000x reference)
.LBB0_2371:
	s_or_b64 exec, exec, s[10:11]
	s_waitcnt vmcnt(0)
	v_readfirstlane_b32 s10, v19
	s_nop 1
	v_add_u32_e32 v54, s10, v18
	v_mov_b32_e32 v254, v54

.LBB0_2378:
	s_and_saveexec_b64 s[2:3], s[8:9]
	s_cbranch_execz .Lqdef9
	s_waitcnt vmcnt(0)
	v_mov_b32_e32 v54, v254
.Lqdef9:
	v_mov_b32_e32 v18, s27
	ds_write_b32 v18, v54
	s_or_b64 exec, exec, s[2:3]
	s_waitcnt lgkmcnt(0)
	s_barrier
	ds_read_b32 v18, v47
	s_waitcnt lgkmcnt(0)
	s_barrier
	v_cmp_le_i32_e64 s[2:3], s28, v18
	v_readfirstlane_b32 s30, v18
	s_and_b64 vcc, exec, s[2:3]
	s_cbranch_vccnz .LBB0_2377
	s_and_saveexec_b64 s[10:11], s[8:9]
	s_cbranch_execz .LBB0_2385
	s_mov_b64 s[14:15], exec
	v_mbcnt_lo_u32_b32 v18, s14, 0
	v_mbcnt_hi_u32_b32 v18, s15, v18
	v_cmp_eq_u32_e32 vcc, 0, v18
	s_and_saveexec_b64 s[12:13], vcc
	s_cbranch_execz .LBB0_2384
	s_bcnt1_i32_b64 s14, s[14:15]
	v_mov_b32_e32 v19, s14
	global_atomic_add v254, v195, v19, s[4:5] sc0
.LBB0_2384:
	s_or_b64 exec, exec, s[12:13]
.LBB0_2385:
	s_or_b64 exec, exec, s[10:11]
	s_ashr_i32 s31, s30, 3
	s_add_i32 s31, s31, s29
	s_cmp_eq_u32 s31, s18
	s_cbranch_scc1 .LBB0_2376
	s_and_saveexec_b64 s[10:11], s[0:1]
	s_cbranch_execz .LBB0_2375
	s_lshl_b32 s12, s31, 6
	s_ashr_i32 s13, s12, 31
	s_lshl_b64 s[12:13], s[12:13], 2
	s_add_u32 s12, s22, s12
	s_addc_u32 s13, s23, s13
	s_mov_b32 s33, 1
	s_branch .LBB0_2389
